# speedup vs baseline: 1.0154x; 1.0154x over previous
; DI unsigned cvtpk(float lo, float hi) { f32x2_t v = {lo, hi}; bf16x2_t b = __builtin_convertvector(v, bf16x2_t); return __builtin_bit_cast(unsigned, b); }
; DI void ln_row(float* yrow, bf16_t* xb, const float* g, const float* b, int lane, float* yout = nullptr) {
;     f32x4* xr = (f32x4*)yrow + lane; f32x4* xo = yout ? (f32x4*)yout + lane : xr;
;     f32x4 v[4]; float s = 0.f;
; #pragma unroll
;     for (int j = 0; j < 4; ++j) { v[j] = xr[64 * j]; s += (v[j].x + v[j].y) + (v[j].z + v[j].w); }
;     const float mean = wave_sum(s) * (1.f / DM); float s2 = 0.f;
; #pragma unroll
;     for (int j = 0; j < 4; ++j) { v[j] = v[j] - mean; s2 += (v[j].x * v[j].x + v[j].y * v[j].y) + (v[j].z * v[j].z + v[j].w * v[j].w); }
;     const float rstd = 1.f / sqrtf(wave_sum(s2) * (1.f / DM) + EPS);
;     u32x2* o8 = (u32x2*)xb + lane;
; #pragma unroll
;     for (int j = 0; j < 4; ++j) {
;         const f32x4 gg = ((const f32x4*)g)[lane + 64 * j], bb = ((const f32x4*)b)[lane + 64 * j];
;         const f32x4 o = v[j] * rstd * gg + bb;
;         xo[64 * j] = o;
;         u32x2 w; w.x = cvtpk(o.x, o.y); w.y = cvtpk(o.z, o.w); o8[64 * j] = w;
;     }
; DI void ln_phase(unsigned char* lds, int l, int which) {
;     ...
;     } else {
;         const int gw = (bid - 8) * 8 + wid, NGW = ((int)gridDim.x - 8) * 8;
;         if (REPS(3) > 1) for (int m = gw; m < MP; m += NGW) ln_row(Y + (size_t)m * DM, (bf16_t*)(ws + WS_OG) + (size_t)m * DM, g, b, lane, (float*)(ws + WS_BIG) + (size_t)m * DM);
;         int m = gw;
;         for (; m + NGW < MP; m += 2 * NGW) ln_row2(Y + (size_t)m * DM, Y + (size_t)(m + NGW) * DM, XB + (size_t)m * DM, XB + (size_t)(m + NGW) * DM, g, b, lane);
;         if (m < MP) ln_row(Y + (size_t)m * DM, XB + (size_t)m * DM, g, b, lane);
.LBB0_327:
	s_or_b64 exec, exec, s[34:35]
	s_mov_b64 s[50:51], s[90:91]
	s_waitcnt lgkmcnt(0)
	s_barrier
	s_load_dwordx8 s[40:47], s[50:51], 0xb8
	v_readlane_b32 s73, v247, 50
	s_mul_i32 s5, s73, 0x3000
	s_mul_hi_i32 s4, s73, 0x3000
	s_waitcnt lgkmcnt(0)
	s_add_u32 s58, s40, s5
	s_addc_u32 s59, s41, s4
	s_add_u32 s60, s42, s5
	v_mov_b32_e32 v163, v212
	s_mov_b32 s72, s2
	s_addc_u32 s61, s43, s4
	s_cmp_gt_i32 s72, 7
	v_and_b32_e32 v1, 63, v163
	v_ashrrev_i32_e32 v162, 6, v163
	s_mov_b64 s[40:41], -1
	s_cbranch_scc0 .LBB0_335
	s_mov_b64 s[52:53], exec
	s_add_u32 s42, s46, 0x3a00000
	s_addc_u32 s43, s47, 0
	v_readfirstlane_b32 s4, v162
	s_lshl_b32 s6, s72, 3
	s_add_i32 s4, s4, s6
	s_sub_i32 s4, s4, 64
	v_readlane_b32 s5, v247, 49
	v_lshlrev_b32_e32 v2, 4, v1
	v_lshlrev_b32_e32 v3, 3, v1
	global_load_dwordx4 v[4:7], v2, s[58:59]
	global_load_dwordx4 v[8:11], v2, s[58:59] offset:1024
	global_load_dwordx4 v[12:15], v2, s[58:59] offset:2048
	global_load_dwordx4 v[16:19], v2, s[58:59] offset:3072
	global_load_dwordx4 v[20:23], v2, s[60:61]
	global_load_dwordx4 v[24:27], v2, s[60:61] offset:1024
	global_load_dwordx4 v[28:31], v2, s[60:61] offset:2048
	global_load_dwordx4 v[32:35], v2, s[60:61] offset:3072
	s_and_b32 s56, s72, 7
	s_lshr_b32 s57, s72, 3
	s_sub_i32 s57, s57, 1
	s_lshl_b32 s57, s57, 3
	v_readfirstlane_b32 s100, v162
	s_add_i32 s57, s57, s100
	s_and_b32 s100, s57, 63
	s_lshr_b32 s57, s57, 6
	s_cmp_lt_u32 s100, 32
	s_cbranch_scc0 .Lmy_pfp0_b
	s_and_b32 s101, s56, 1
	s_lshl_b32 s101, s101, 8
	s_lshl_b32 s100, s100, 3
	s_add_i32 s100, s100, s101
	s_mul_i32 s100, s100, 5632
	s_add_u32 s48, s46, 0x1b400000
	s_addc_u32 s49, s47, 0
	s_branch .Lmy_pfp0_j
.Lmy_pfp0_b:
	s_sub_i32 s100, s100, 32
	s_lshr_b32 s101, s56, 1
	s_lshl_b32 s101, s101, 8
	s_lshl_b32 s100, s100, 3
	s_add_i32 s100, s100, s101
	s_mul_i32 s100, s100, 5632
	s_add_u32 s48, s46, 0xc00000
	s_addc_u32 s49, s47, 0
.Lmy_pfp0_j:
	s_add_u32 s48, s48, s100
	s_addc_u32 s49, s49, 0
	s_add_i32 s56, s57, 0
	v_lshrrev_b32_e32 v108, 3, v1
	v_mul_u32_u24_e32 v108, 5632, v108
	v_and_b32_e32 v109, 7, v1
	v_lshl_add_u32 v108, v109, 4, v108
	s_lshl_b32 s34, s5, 12
	s_lshl_b32 s35, s5, 11
	s_lshl_b32 s6, s4, 12
	s_add_u32 s8, s44, s6
	s_addc_u32 s9, s45, 0
	s_lshl_b32 s6, s4, 11
	s_add_u32 s10, s42, s6
	s_addc_u32 s11, s43, 0
	s_mov_b32 s6, s8
	s_mov_b32 s7, s9
	s_mov_b32 s54, s4
	global_load_dwordx4 v[36:39], v2, s[6:7] nt
	global_load_dwordx4 v[40:43], v2, s[6:7] offset:1024 nt
	global_load_dwordx4 v[44:47], v2, s[6:7] offset:2048 nt
	global_load_dwordx4 v[48:51], v2, s[6:7] offset:3072 nt
	s_add_u32 s6, s6, s34
	s_addc_u32 s7, s7, 0
	s_add_i32 s54, s54, s5
	global_load_dwordx4 v[52:55], v2, s[6:7] nt
	global_load_dwordx4 v[56:59], v2, s[6:7] offset:1024 nt
	global_load_dwordx4 v[60:63], v2, s[6:7] offset:2048 nt
	global_load_dwordx4 v[64:67], v2, s[6:7] offset:3072 nt
	s_add_u32 s6, s6, s34
	s_addc_u32 s7, s7, 0
	s_add_i32 s54, s54, s5
	s_waitcnt vmcnt(4)
.Lmy_lnp0_b0:
	s_cmp_ge_i32 s54, 0x8000
	s_cbranch_scc1 .Lmy_lnp0_n0
	global_load_dwordx4 v[68:71], v2, s[6:7] nt
	global_load_dwordx4 v[72:75], v2, s[6:7] offset:1024 nt
	global_load_dwordx4 v[76:79], v2, s[6:7] offset:2048 nt
	global_load_dwordx4 v[80:83], v2, s[6:7] offset:3072 nt
	s_add_u32 s6, s6, s34
	s_addc_u32 s7, s7, 0
	s_add_i32 s54, s54, s5
.Lmy_lnp0_n0:
	s_add_i32 s100, s56, 0
	s_min_u32 s100, s100, 43
	s_lshl_b32 s100, s100, 7
	s_add_u32 s100, s48, s100
	s_addc_u32 s101, s49, 0
	global_load_dwordx4 v[110:113], v108, s[100:101]
	s_add_i32 s56, s56, 4
	s_waitcnt vmcnt(18)
	v_add_f32_e32 v84, v36, v37
	v_add_f32_e32 v85, v38, v39
	v_add_f32_e32 v86, v40, v41
	v_add_f32_e32 v87, v42, v43
	v_add_f32_e32 v88, v44, v45
	v_add_f32_e32 v89, v46, v47
	v_add_f32_e32 v90, v48, v49
	v_add_f32_e32 v91, v50, v51
	v_add_f32_e32 v84, v84, v85
	v_add_f32_e32 v86, v86, v87
	v_add_f32_e32 v88, v88, v89
	v_add_f32_e32 v90, v90, v91
	v_add_f32_e32 v84, v84, v86
	v_add_f32_e32 v88, v88, v90
	v_add_f32_e32 v84, v84, v88
	s_nop 1
	v_add_f32_dpp v84, v84, v84 quad_perm:[1,0,3,2] row_mask:0xf bank_mask:0xf
	s_nop 1
	v_add_f32_dpp v84, v84, v84 quad_perm:[2,3,0,1] row_mask:0xf bank_mask:0xf
	s_nop 1
	v_add_f32_dpp v84, v84, v84 row_half_mirror row_mask:0xf bank_mask:0xf
	s_nop 1
	v_add_f32_dpp v84, v84, v84 row_mirror row_mask:0xf bank_mask:0xf
	s_nop 1
	v_add_f32_dpp v84, v84, v84 row_bcast:15 row_mask:0xa bank_mask:0xf
	s_nop 1
	v_add_f32_dpp v84, v84, v84 row_bcast:31 row_mask:0xc bank_mask:0xf
	s_nop 1
	v_readlane_b32 s55, v84, 63
	s_nop 1
	v_mov_b32_e32 v85, s55
	v_mul_f32_e32 v85, 0x3a800000, v85
	v_sub_f32_e32 v36, v36, v85
	v_sub_f32_e32 v37, v37, v85
	v_sub_f32_e32 v38, v38, v85
	v_sub_f32_e32 v39, v39, v85
	v_sub_f32_e32 v40, v40, v85
	v_sub_f32_e32 v41, v41, v85
	v_sub_f32_e32 v42, v42, v85
	v_sub_f32_e32 v43, v43, v85
	v_sub_f32_e32 v44, v44, v85
	v_sub_f32_e32 v45, v45, v85
	v_sub_f32_e32 v46, v46, v85
	v_sub_f32_e32 v47, v47, v85
	v_sub_f32_e32 v48, v48, v85
	v_sub_f32_e32 v49, v49, v85
	v_sub_f32_e32 v50, v50, v85
	v_sub_f32_e32 v51, v51, v85
	v_mul_f32_e32 v88, v36, v36
	v_mul_f32_e32 v89, v37, v37
	v_mul_f32_e32 v90, v38, v38
	v_mul_f32_e32 v91, v39, v39
	v_fmac_f32_e32 v88, v40, v40
	v_fmac_f32_e32 v89, v41, v41
	v_fmac_f32_e32 v90, v42, v42
	v_fmac_f32_e32 v91, v43, v43
	v_fmac_f32_e32 v88, v44, v44
	v_fmac_f32_e32 v89, v45, v45
	v_fmac_f32_e32 v90, v46, v46
	v_fmac_f32_e32 v91, v47, v47
	v_fmac_f32_e32 v88, v48, v48
	v_fmac_f32_e32 v89, v49, v49
	v_fmac_f32_e32 v90, v50, v50
	v_fmac_f32_e32 v91, v51, v51
	v_add_f32_e32 v88, v88, v89
	v_add_f32_e32 v90, v90, v91
	v_add_f32_e32 v88, v88, v90
	s_nop 1
; DI unsigned cvtpk(float lo, float hi) { f32x2_t v = {lo, hi}; bf16x2_t b = __builtin_convertvector(v, bf16x2_t); return __builtin_bit_cast(unsigned, b); }
; DI void ln_row(float* yrow, bf16_t* xb, const float* g, const float* b, int lane, float* yout = nullptr) {
;     f32x4* xr = (f32x4*)yrow + lane; f32x4* xo = yout ? (f32x4*)yout + lane : xr;
;     f32x4 v[4]; float s = 0.f;
; #pragma unroll
;     for (int j = 0; j < 4; ++j) { v[j] = xr[64 * j]; s += (v[j].x + v[j].y) + (v[j].z + v[j].w); }
;     const float mean = wave_sum(s) * (1.f / DM); float s2 = 0.f;
; #pragma unroll
;     for (int j = 0; j < 4; ++j) { v[j] = v[j] - mean; s2 += (v[j].x * v[j].x + v[j].y * v[j].y) + (v[j].z * v[j].z + v[j].w * v[j].w); }
;     const float rstd = 1.f / sqrtf(wave_sum(s2) * (1.f / DM) + EPS);
;     u32x2* o8 = (u32x2*)xb + lane;
; #pragma unroll
;     for (int j = 0; j < 4; ++j) {
;         const f32x4 gg = ((const f32x4*)g)[lane + 64 * j], bb = ((const f32x4*)b)[lane + 64 * j];
;         const f32x4 o = v[j] * rstd * gg + bb;
;         xo[64 * j] = o;
;         u32x2 w; w.x = cvtpk(o.x, o.y); w.y = cvtpk(o.z, o.w); o8[64 * j] = w;
;     }
	v_add_f32_dpp v88, v88, v88 quad_perm:[1,0,3,2] row_mask:0xf bank_mask:0xf
	s_nop 1
	v_add_f32_dpp v88, v88, v88 quad_perm:[2,3,0,1] row_mask:0xf bank_mask:0xf
	s_nop 1
	v_add_f32_dpp v88, v88, v88 row_half_mirror row_mask:0xf bank_mask:0xf
	s_nop 1
	v_add_f32_dpp v88, v88, v88 row_mirror row_mask:0xf bank_mask:0xf
	s_nop 1
	v_add_f32_dpp v88, v88, v88 row_bcast:15 row_mask:0xa bank_mask:0xf
	s_nop 1
	v_add_f32_dpp v88, v88, v88 row_bcast:31 row_mask:0xc bank_mask:0xf
	s_nop 1
	v_readlane_b32 s55, v88, 63
	s_nop 1
	v_mov_b32_e32 v89, s55
	v_fmamk_f32 v89, v89, 0x3a800000, v214
	v_rsq_f32_e32 v90, v89
	s_nop 0
	v_mul_f32_e32 v91, v89, v90
	v_mul_f32_e32 v91, v91, v90
	v_mul_f32_e32 v91, -0.5, v91
	v_add_f32_e32 v91, 0x3fc00000, v91
	v_mul_f32_e32 v90, v90, v91
	v_pk_mul_f32 v[36:37], v[36:37], v[90:91] op_sel_hi:[1,0]
	v_pk_mul_f32 v[38:39], v[38:39], v[90:91] op_sel_hi:[1,0]
	v_pk_mul_f32 v[40:41], v[40:41], v[90:91] op_sel_hi:[1,0]
	v_pk_mul_f32 v[42:43], v[42:43], v[90:91] op_sel_hi:[1,0]
	v_pk_mul_f32 v[44:45], v[44:45], v[90:91] op_sel_hi:[1,0]
	v_pk_mul_f32 v[46:47], v[46:47], v[90:91] op_sel_hi:[1,0]
	v_pk_mul_f32 v[48:49], v[48:49], v[90:91] op_sel_hi:[1,0]
	v_pk_mul_f32 v[50:51], v[50:51], v[90:91] op_sel_hi:[1,0]
	v_pk_fma_f32 v[36:37], v[36:37], v[4:5], v[20:21]
	v_pk_fma_f32 v[38:39], v[38:39], v[6:7], v[22:23]
	v_pk_fma_f32 v[40:41], v[40:41], v[8:9], v[24:25]
	v_pk_fma_f32 v[42:43], v[42:43], v[10:11], v[26:27]
	v_pk_fma_f32 v[44:45], v[44:45], v[12:13], v[28:29]
	v_pk_fma_f32 v[46:47], v[46:47], v[14:15], v[30:31]
	v_pk_fma_f32 v[48:49], v[48:49], v[16:17], v[32:33]
	v_pk_fma_f32 v[50:51], v[50:51], v[18:19], v[34:35]
	v_cvt_pk_bf16_f32 v100, v36, v37
	v_cvt_pk_bf16_f32 v101, v38, v39
	v_cvt_pk_bf16_f32 v102, v40, v41
	v_cvt_pk_bf16_f32 v103, v42, v43
	v_cvt_pk_bf16_f32 v104, v44, v45
	v_cvt_pk_bf16_f32 v105, v46, v47
	v_cvt_pk_bf16_f32 v106, v48, v49
	v_cvt_pk_bf16_f32 v107, v50, v51
	global_store_dwordx4 v2, v[36:39], s[8:9] nt
	global_store_dwordx4 v2, v[40:43], s[8:9] offset:1024 nt
	global_store_dwordx4 v2, v[44:47], s[8:9] offset:2048 nt
	global_store_dwordx4 v2, v[48:51], s[8:9] offset:3072 nt
	global_store_dwordx2 v3, v[100:101], s[10:11] nt
	global_store_dwordx2 v3, v[102:103], s[10:11] offset:512 nt
	global_store_dwordx2 v3, v[104:105], s[10:11] offset:1024 nt
	global_store_dwordx2 v3, v[106:107], s[10:11] offset:1536 nt
	s_add_u32 s8, s8, s34
	s_addc_u32 s9, s9, 0
	s_add_u32 s10, s10, s35
	s_addc_u32 s11, s11, 0
	s_add_i32 s4, s4, s5
	s_cmp_ge_i32 s4, 0x8000
	s_cbranch_scc1 .Lmy_lnp0_done
.Lmy_lnp0_b1:
	s_cmp_ge_i32 s54, 0x8000
	s_cbranch_scc1 .Lmy_lnp0_n1
	global_load_dwordx4 v[36:39], v2, s[6:7] nt
	global_load_dwordx4 v[40:43], v2, s[6:7] offset:1024 nt
	global_load_dwordx4 v[44:47], v2, s[6:7] offset:2048 nt
	global_load_dwordx4 v[48:51], v2, s[6:7] offset:3072 nt
	s_add_u32 s6, s6, s34
	s_addc_u32 s7, s7, 0
	s_add_i32 s54, s54, s5
.Lmy_lnp0_n1:
	s_add_i32 s100, s56, 0
	s_min_u32 s100, s100, 43
	s_lshl_b32 s100, s100, 7
	s_add_u32 s100, s48, s100
	s_addc_u32 s101, s49, 0
	global_load_dwordx4 v[110:113], v108, s[100:101]
	s_add_i32 s56, s56, 4
	s_waitcnt vmcnt(18)
	v_add_f32_e32 v84, v52, v53
	v_add_f32_e32 v85, v54, v55
	v_add_f32_e32 v86, v56, v57
	v_add_f32_e32 v87, v58, v59
	v_add_f32_e32 v88, v60, v61
	v_add_f32_e32 v89, v62, v63
	v_add_f32_e32 v90, v64, v65
	v_add_f32_e32 v91, v66, v67
	v_add_f32_e32 v84, v84, v85
	v_add_f32_e32 v86, v86, v87
	v_add_f32_e32 v88, v88, v89
	v_add_f32_e32 v90, v90, v91
	v_add_f32_e32 v84, v84, v86
	v_add_f32_e32 v88, v88, v90
	v_add_f32_e32 v84, v84, v88
	s_nop 1
	v_add_f32_dpp v84, v84, v84 quad_perm:[1,0,3,2] row_mask:0xf bank_mask:0xf
	s_nop 1
	v_add_f32_dpp v84, v84, v84 quad_perm:[2,3,0,1] row_mask:0xf bank_mask:0xf
	s_nop 1
	v_add_f32_dpp v84, v84, v84 row_half_mirror row_mask:0xf bank_mask:0xf
	s_nop 1
	v_add_f32_dpp v84, v84, v84 row_mirror row_mask:0xf bank_mask:0xf
	s_nop 1
	v_add_f32_dpp v84, v84, v84 row_bcast:15 row_mask:0xa bank_mask:0xf
	s_nop 1
	v_add_f32_dpp v84, v84, v84 row_bcast:31 row_mask:0xc bank_mask:0xf
	s_nop 1
	v_readlane_b32 s55, v84, 63
	s_nop 1
	v_mov_b32_e32 v85, s55
	v_mul_f32_e32 v85, 0x3a800000, v85
	v_sub_f32_e32 v52, v52, v85
	v_sub_f32_e32 v53, v53, v85
	v_sub_f32_e32 v54, v54, v85
	v_sub_f32_e32 v55, v55, v85
	v_sub_f32_e32 v56, v56, v85
	v_sub_f32_e32 v57, v57, v85
	v_sub_f32_e32 v58, v58, v85
	v_sub_f32_e32 v59, v59, v85
	v_sub_f32_e32 v60, v60, v85
	v_sub_f32_e32 v61, v61, v85
	v_sub_f32_e32 v62, v62, v85
	v_sub_f32_e32 v63, v63, v85
	v_sub_f32_e32 v64, v64, v85
	v_sub_f32_e32 v65, v65, v85
	v_sub_f32_e32 v66, v66, v85
	v_sub_f32_e32 v67, v67, v85
	v_mul_f32_e32 v88, v52, v52
	v_mul_f32_e32 v89, v53, v53
	v_mul_f32_e32 v90, v54, v54
	v_mul_f32_e32 v91, v55, v55
	v_fmac_f32_e32 v88, v56, v56
	v_fmac_f32_e32 v89, v57, v57
	v_fmac_f32_e32 v90, v58, v58
	v_fmac_f32_e32 v91, v59, v59
	v_fmac_f32_e32 v88, v60, v60
	v_fmac_f32_e32 v89, v61, v61
	v_fmac_f32_e32 v90, v62, v62
	v_fmac_f32_e32 v91, v63, v63
	v_fmac_f32_e32 v88, v64, v64
	v_fmac_f32_e32 v89, v65, v65
	v_fmac_f32_e32 v90, v66, v66
	v_fmac_f32_e32 v91, v67, v67
	v_add_f32_e32 v88, v88, v89
	v_add_f32_e32 v90, v90, v91
	v_add_f32_e32 v88, v88, v90
	s_nop 1
	v_add_f32_dpp v88, v88, v88 quad_perm:[1,0,3,2] row_mask:0xf bank_mask:0xf
	s_nop 1
	v_add_f32_dpp v88, v88, v88 quad_perm:[2,3,0,1] row_mask:0xf bank_mask:0xf
	s_nop 1
	v_add_f32_dpp v88, v88, v88 row_half_mirror row_mask:0xf bank_mask:0xf
	s_nop 1
	v_add_f32_dpp v88, v88, v88 row_mirror row_mask:0xf bank_mask:0xf
	s_nop 1
	v_add_f32_dpp v88, v88, v88 row_bcast:15 row_mask:0xa bank_mask:0xf
	s_nop 1
; DI unsigned cvtpk(float lo, float hi) { f32x2_t v = {lo, hi}; bf16x2_t b = __builtin_convertvector(v, bf16x2_t); return __builtin_bit_cast(unsigned, b); }
; DI void ln_row(float* yrow, bf16_t* xb, const float* g, const float* b, int lane, float* yout = nullptr) {
;     f32x4* xr = (f32x4*)yrow + lane; f32x4* xo = yout ? (f32x4*)yout + lane : xr;
;     f32x4 v[4]; float s = 0.f;
; #pragma unroll
;     for (int j = 0; j < 4; ++j) { v[j] = xr[64 * j]; s += (v[j].x + v[j].y) + (v[j].z + v[j].w); }
;     const float mean = wave_sum(s) * (1.f / DM); float s2 = 0.f;
; #pragma unroll
;     for (int j = 0; j < 4; ++j) { v[j] = v[j] - mean; s2 += (v[j].x * v[j].x + v[j].y * v[j].y) + (v[j].z * v[j].z + v[j].w * v[j].w); }
;     const float rstd = 1.f / sqrtf(wave_sum(s2) * (1.f / DM) + EPS);
;     u32x2* o8 = (u32x2*)xb + lane;
; #pragma unroll
;     for (int j = 0; j < 4; ++j) {
;         const f32x4 gg = ((const f32x4*)g)[lane + 64 * j], bb = ((const f32x4*)b)[lane + 64 * j];
;         const f32x4 o = v[j] * rstd * gg + bb;
;         xo[64 * j] = o;
;         u32x2 w; w.x = cvtpk(o.x, o.y); w.y = cvtpk(o.z, o.w); o8[64 * j] = w;
;     }
	v_add_f32_dpp v88, v88, v88 row_bcast:31 row_mask:0xc bank_mask:0xf
	s_nop 1
	v_readlane_b32 s55, v88, 63
	s_nop 1
	v_mov_b32_e32 v89, s55
	v_fmamk_f32 v89, v89, 0x3a800000, v214
	v_rsq_f32_e32 v90, v89
	s_nop 0
	v_mul_f32_e32 v91, v89, v90
	v_mul_f32_e32 v91, v91, v90
	v_mul_f32_e32 v91, -0.5, v91
	v_add_f32_e32 v91, 0x3fc00000, v91
	v_mul_f32_e32 v90, v90, v91
	v_pk_mul_f32 v[52:53], v[52:53], v[90:91] op_sel_hi:[1,0]
	v_pk_mul_f32 v[54:55], v[54:55], v[90:91] op_sel_hi:[1,0]
	v_pk_mul_f32 v[56:57], v[56:57], v[90:91] op_sel_hi:[1,0]
	v_pk_mul_f32 v[58:59], v[58:59], v[90:91] op_sel_hi:[1,0]
	v_pk_mul_f32 v[60:61], v[60:61], v[90:91] op_sel_hi:[1,0]
	v_pk_mul_f32 v[62:63], v[62:63], v[90:91] op_sel_hi:[1,0]
	v_pk_mul_f32 v[64:65], v[64:65], v[90:91] op_sel_hi:[1,0]
	v_pk_mul_f32 v[66:67], v[66:67], v[90:91] op_sel_hi:[1,0]
	v_pk_fma_f32 v[52:53], v[52:53], v[4:5], v[20:21]
	v_pk_fma_f32 v[54:55], v[54:55], v[6:7], v[22:23]
	v_pk_fma_f32 v[56:57], v[56:57], v[8:9], v[24:25]
	v_pk_fma_f32 v[58:59], v[58:59], v[10:11], v[26:27]
	v_pk_fma_f32 v[60:61], v[60:61], v[12:13], v[28:29]
	v_pk_fma_f32 v[62:63], v[62:63], v[14:15], v[30:31]
	v_pk_fma_f32 v[64:65], v[64:65], v[16:17], v[32:33]
	v_pk_fma_f32 v[66:67], v[66:67], v[18:19], v[34:35]
	v_cvt_pk_bf16_f32 v100, v52, v53
	v_cvt_pk_bf16_f32 v101, v54, v55
	v_cvt_pk_bf16_f32 v102, v56, v57
	v_cvt_pk_bf16_f32 v103, v58, v59
	v_cvt_pk_bf16_f32 v104, v60, v61
	v_cvt_pk_bf16_f32 v105, v62, v63
	v_cvt_pk_bf16_f32 v106, v64, v65
	v_cvt_pk_bf16_f32 v107, v66, v67
	global_store_dwordx4 v2, v[52:55], s[8:9] nt
	global_store_dwordx4 v2, v[56:59], s[8:9] offset:1024 nt
	global_store_dwordx4 v2, v[60:63], s[8:9] offset:2048 nt
	global_store_dwordx4 v2, v[64:67], s[8:9] offset:3072 nt
	global_store_dwordx2 v3, v[100:101], s[10:11] nt
	global_store_dwordx2 v3, v[102:103], s[10:11] offset:512 nt
	global_store_dwordx2 v3, v[104:105], s[10:11] offset:1024 nt
	global_store_dwordx2 v3, v[106:107], s[10:11] offset:1536 nt
	s_add_u32 s8, s8, s34
	s_addc_u32 s9, s9, 0
	s_add_u32 s10, s10, s35
	s_addc_u32 s11, s11, 0
	s_add_i32 s4, s4, s5
	s_cmp_ge_i32 s4, 0x8000
	s_cbranch_scc1 .Lmy_lnp0_done
.Lmy_lnp0_b2:
	s_cmp_ge_i32 s54, 0x8000
	s_cbranch_scc1 .Lmy_lnp0_n2
	global_load_dwordx4 v[52:55], v2, s[6:7] nt
	global_load_dwordx4 v[56:59], v2, s[6:7] offset:1024 nt
	global_load_dwordx4 v[60:63], v2, s[6:7] offset:2048 nt
	global_load_dwordx4 v[64:67], v2, s[6:7] offset:3072 nt
	s_add_u32 s6, s6, s34
	s_addc_u32 s7, s7, 0
	s_add_i32 s54, s54, s5
; DI unsigned cvtpk(float lo, float hi) { f32x2_t v = {lo, hi}; bf16x2_t b = __builtin_convertvector(v, bf16x2_t); return __builtin_bit_cast(unsigned, b); }
; DI void ln_row(float* yrow, bf16_t* xb, const float* g, const float* b, int lane, float* yout = nullptr) {
;     f32x4* xr = (f32x4*)yrow + lane; f32x4* xo = yout ? (f32x4*)yout + lane : xr;
;     f32x4 v[4]; float s = 0.f;
; #pragma unroll
;     for (int j = 0; j < 4; ++j) { v[j] = xr[64 * j]; s += (v[j].x + v[j].y) + (v[j].z + v[j].w); }
;     const float mean = wave_sum(s) * (1.f / DM); float s2 = 0.f;
; #pragma unroll
;     for (int j = 0; j < 4; ++j) { v[j] = v[j] - mean; s2 += (v[j].x * v[j].x + v[j].y * v[j].y) + (v[j].z * v[j].z + v[j].w * v[j].w); }
;     const float rstd = 1.f / sqrtf(wave_sum(s2) * (1.f / DM) + EPS);
;     u32x2* o8 = (u32x2*)xb + lane;
; #pragma unroll
;     for (int j = 0; j < 4; ++j) {
;         const f32x4 gg = ((const f32x4*)g)[lane + 64 * j], bb = ((const f32x4*)b)[lane + 64 * j];
;         const f32x4 o = v[j] * rstd * gg + bb;
;         xo[64 * j] = o;
;         u32x2 w; w.x = cvtpk(o.x, o.y); w.y = cvtpk(o.z, o.w); o8[64 * j] = w;
;     }
; DI void ln_phase(unsigned char* lds, int l, int which) {
;     ...
;         int m = gw;
;         for (; m + NGW < MP; m += 2 * NGW) ln_row2(Y + (size_t)m * DM, Y + (size_t)(m + NGW) * DM, XB + (size_t)m * DM, XB + (size_t)(m + NGW) * DM, g, b, lane);
;         if (m < MP) ln_row(Y + (size_t)m * DM, XB + (size_t)m * DM, g, b, lane);
.Lmy_lnp0_n2:
	s_add_i32 s100, s56, 0
	s_min_u32 s100, s100, 43
	s_lshl_b32 s100, s100, 7
	s_add_u32 s100, s48, s100
	s_addc_u32 s101, s49, 0
	global_load_dwordx4 v[110:113], v108, s[100:101]
	s_add_i32 s56, s56, 4
	s_waitcnt vmcnt(18)
	v_add_f32_e32 v84, v68, v69
	v_add_f32_e32 v85, v70, v71
	v_add_f32_e32 v86, v72, v73
	v_add_f32_e32 v87, v74, v75
	v_add_f32_e32 v88, v76, v77
	v_add_f32_e32 v89, v78, v79
	v_add_f32_e32 v90, v80, v81
	v_add_f32_e32 v91, v82, v83
	v_add_f32_e32 v84, v84, v85
	v_add_f32_e32 v86, v86, v87
	v_add_f32_e32 v88, v88, v89
	v_add_f32_e32 v90, v90, v91
	v_add_f32_e32 v84, v84, v86
	v_add_f32_e32 v88, v88, v90
	v_add_f32_e32 v84, v84, v88
	s_nop 1
	v_add_f32_dpp v84, v84, v84 quad_perm:[1,0,3,2] row_mask:0xf bank_mask:0xf
	s_nop 1
	v_add_f32_dpp v84, v84, v84 quad_perm:[2,3,0,1] row_mask:0xf bank_mask:0xf
	s_nop 1
	v_add_f32_dpp v84, v84, v84 row_half_mirror row_mask:0xf bank_mask:0xf
	s_nop 1
	v_add_f32_dpp v84, v84, v84 row_mirror row_mask:0xf bank_mask:0xf
	s_nop 1
	v_add_f32_dpp v84, v84, v84 row_bcast:15 row_mask:0xa bank_mask:0xf
	s_nop 1
	v_add_f32_dpp v84, v84, v84 row_bcast:31 row_mask:0xc bank_mask:0xf
	s_nop 1
	v_readlane_b32 s55, v84, 63
	s_nop 1
	v_mov_b32_e32 v85, s55
	v_mul_f32_e32 v85, 0x3a800000, v85
	v_sub_f32_e32 v68, v68, v85
	v_sub_f32_e32 v69, v69, v85
	v_sub_f32_e32 v70, v70, v85
	v_sub_f32_e32 v71, v71, v85
	v_sub_f32_e32 v72, v72, v85
	v_sub_f32_e32 v73, v73, v85
	v_sub_f32_e32 v74, v74, v85
	v_sub_f32_e32 v75, v75, v85
	v_sub_f32_e32 v76, v76, v85
	v_sub_f32_e32 v77, v77, v85
	v_sub_f32_e32 v78, v78, v85
	v_sub_f32_e32 v79, v79, v85
	v_sub_f32_e32 v80, v80, v85
	v_sub_f32_e32 v81, v81, v85
	v_sub_f32_e32 v82, v82, v85
	v_sub_f32_e32 v83, v83, v85
	v_mul_f32_e32 v88, v68, v68
	v_mul_f32_e32 v89, v69, v69
	v_mul_f32_e32 v90, v70, v70
	v_mul_f32_e32 v91, v71, v71
	v_fmac_f32_e32 v88, v72, v72
	v_fmac_f32_e32 v89, v73, v73
	v_fmac_f32_e32 v90, v74, v74
	v_fmac_f32_e32 v91, v75, v75
	v_fmac_f32_e32 v88, v76, v76
	v_fmac_f32_e32 v89, v77, v77
	v_fmac_f32_e32 v90, v78, v78
	v_fmac_f32_e32 v91, v79, v79
	v_fmac_f32_e32 v88, v80, v80
	v_fmac_f32_e32 v89, v81, v81
	v_fmac_f32_e32 v90, v82, v82
	v_fmac_f32_e32 v91, v83, v83
	v_add_f32_e32 v88, v88, v89
	v_add_f32_e32 v90, v90, v91
	v_add_f32_e32 v88, v88, v90
	s_nop 1
	v_add_f32_dpp v88, v88, v88 quad_perm:[1,0,3,2] row_mask:0xf bank_mask:0xf
	s_nop 1
	v_add_f32_dpp v88, v88, v88 quad_perm:[2,3,0,1] row_mask:0xf bank_mask:0xf
	s_nop 1
	v_add_f32_dpp v88, v88, v88 row_half_mirror row_mask:0xf bank_mask:0xf
	s_nop 1
	v_add_f32_dpp v88, v88, v88 row_mirror row_mask:0xf bank_mask:0xf
	s_nop 1
	v_add_f32_dpp v88, v88, v88 row_bcast:15 row_mask:0xa bank_mask:0xf
	s_nop 1
	v_add_f32_dpp v88, v88, v88 row_bcast:31 row_mask:0xc bank_mask:0xf
	s_nop 1
	v_readlane_b32 s55, v88, 63
	s_nop 1
	v_mov_b32_e32 v89, s55
	v_fmamk_f32 v89, v89, 0x3a800000, v214
	v_rsq_f32_e32 v90, v89
	s_nop 0
	v_mul_f32_e32 v91, v89, v90
	v_mul_f32_e32 v91, v91, v90
	v_mul_f32_e32 v91, -0.5, v91
	v_add_f32_e32 v91, 0x3fc00000, v91
	v_mul_f32_e32 v90, v90, v91
	v_pk_mul_f32 v[68:69], v[68:69], v[90:91] op_sel_hi:[1,0]
	v_pk_mul_f32 v[70:71], v[70:71], v[90:91] op_sel_hi:[1,0]
	v_pk_mul_f32 v[72:73], v[72:73], v[90:91] op_sel_hi:[1,0]
	v_pk_mul_f32 v[74:75], v[74:75], v[90:91] op_sel_hi:[1,0]
	v_pk_mul_f32 v[76:77], v[76:77], v[90:91] op_sel_hi:[1,0]
	v_pk_mul_f32 v[78:79], v[78:79], v[90:91] op_sel_hi:[1,0]
	v_pk_mul_f32 v[80:81], v[80:81], v[90:91] op_sel_hi:[1,0]
	v_pk_mul_f32 v[82:83], v[82:83], v[90:91] op_sel_hi:[1,0]
	v_pk_fma_f32 v[68:69], v[68:69], v[4:5], v[20:21]
	v_pk_fma_f32 v[70:71], v[70:71], v[6:7], v[22:23]
	v_pk_fma_f32 v[72:73], v[72:73], v[8:9], v[24:25]
	v_pk_fma_f32 v[74:75], v[74:75], v[10:11], v[26:27]
	v_pk_fma_f32 v[76:77], v[76:77], v[12:13], v[28:29]
	v_pk_fma_f32 v[78:79], v[78:79], v[14:15], v[30:31]
	v_pk_fma_f32 v[80:81], v[80:81], v[16:17], v[32:33]
	v_pk_fma_f32 v[82:83], v[82:83], v[18:19], v[34:35]
	v_cvt_pk_bf16_f32 v100, v68, v69
	v_cvt_pk_bf16_f32 v101, v70, v71
	v_cvt_pk_bf16_f32 v102, v72, v73
	v_cvt_pk_bf16_f32 v103, v74, v75
	v_cvt_pk_bf16_f32 v104, v76, v77
	v_cvt_pk_bf16_f32 v105, v78, v79
	v_cvt_pk_bf16_f32 v106, v80, v81
	v_cvt_pk_bf16_f32 v107, v82, v83
	global_store_dwordx4 v2, v[68:71], s[8:9] nt
	global_store_dwordx4 v2, v[72:75], s[8:9] offset:1024 nt
	global_store_dwordx4 v2, v[76:79], s[8:9] offset:2048 nt
	global_store_dwordx4 v2, v[80:83], s[8:9] offset:3072 nt
	global_store_dwordx2 v3, v[100:101], s[10:11] nt
	global_store_dwordx2 v3, v[102:103], s[10:11] offset:512 nt
	global_store_dwordx2 v3, v[104:105], s[10:11] offset:1024 nt
	global_store_dwordx2 v3, v[106:107], s[10:11] offset:1536 nt
	s_add_u32 s8, s8, s34
	s_addc_u32 s9, s9, 0
	s_add_u32 s10, s10, s35
	s_addc_u32 s11, s11, 0
	s_add_i32 s4, s4, s5
	s_cmp_ge_i32 s4, 0x8000
	s_cbranch_scc1 .Lmy_lnp0_done
	s_branch .Lmy_lnp0_b0
.Lmy_lnp0_done:
.LBB0_334:
	s_or_b64 exec, exec, s[52:53]
	s_mov_b64 s[40:41], 0

; #define PHASE_BEGIN KArg pp = kargs(); unsigned char* ws = pp->ws; int ll = l; asm volatile("" : "+s"(ll)); (void)ws; (void)ll;
; DI void ln_phase(unsigned char* lds, int l, int which) {
;     PHASE_BEGIN
;     int tid_l = threadIdx.x; asm volatile("" : "+v"(tid_l));
;     int bid_l = blockIdx.x; asm volatile("" : "+s"(bid_l));
;     const int lane = tid_l & 63, wid = tid_l >> 6, bid = bid_l;
;     const float* g = pp->in[23] + ((size_t)ll * 3 + which) * DM; const float* b = pp->in[24] + ((size_t)ll * 3 + which) * DM;
;     float* Y = B_Y; bf16_t* XB = B_XB;
;     ...
;     } else {
;         const int gw = (bid - 8) * 8 + wid, NGW = ((int)gridDim.x - 8) * 8;
;         if (REPS(3) > 1) for (int m = gw; m < MP; m += NGW) ln_row(Y + (size_t)m * DM, (bf16_t*)(ws + WS_OG) + (size_t)m * DM, g, b, lane, (float*)(ws + WS_BIG) + (size_t)m * DM);
;         int m = gw;
;         for (; m + NGW < MP; m += 2 * NGW) ln_row2(Y + (size_t)m * DM, Y + (size_t)(m + NGW) * DM, XB + (size_t)m * DM, XB + (size_t)(m + NGW) * DM, g, b, lane);
;         if (m < MP) ln_row(Y + (size_t)m * DM, XB + (size_t)m * DM, g, b, lane);
.LBB0_2128:
	s_or_b64 exec, exec, s[34:35]
	s_mov_b64 s[4:5], s[90:91]
	s_waitcnt lgkmcnt(0)
	s_barrier
	s_load_dwordx8 s[40:47], s[4:5], 0xb8
	v_readlane_b32 s70, v247, 50
	s_mul_i32 s5, s70, 0x3000
	s_mul_hi_i32 s4, s70, 0x3000
	s_add_u32 s5, s5, 0x1000
	s_addc_u32 s4, s4, 0
	s_waitcnt lgkmcnt(0)
	s_add_u32 s56, s40, s5
	s_addc_u32 s57, s41, s4
	s_add_u32 s48, s42, s5
	v_mov_b32_e32 v163, v212
	s_mov_b32 s38, s2
	s_addc_u32 s49, s43, s4
	s_cmp_gt_i32 s38, 7
	v_and_b32_e32 v1, 63, v163
	v_ashrrev_i32_e32 v162, 6, v163
	s_mov_b64 s[40:41], -1
	s_cbranch_scc0 .LBB0_2136
	s_mov_b64 s[50:51], exec
	s_add_u32 s42, s46, 0x3a00000
	s_addc_u32 s43, s47, 0
	v_readfirstlane_b32 s4, v162
	s_lshl_b32 s6, s38, 3
	s_add_i32 s4, s4, s6
	s_sub_i32 s4, s4, 64
	v_readlane_b32 s5, v247, 49
	v_lshlrev_b32_e32 v2, 4, v1
	v_lshlrev_b32_e32 v3, 3, v1
	global_load_dwordx4 v[4:7], v2, s[56:57]
	global_load_dwordx4 v[8:11], v2, s[56:57] offset:1024
	global_load_dwordx4 v[12:15], v2, s[56:57] offset:2048
	global_load_dwordx4 v[16:19], v2, s[56:57] offset:3072
	global_load_dwordx4 v[20:23], v2, s[48:49]
	global_load_dwordx4 v[24:27], v2, s[48:49] offset:1024
	global_load_dwordx4 v[28:31], v2, s[48:49] offset:2048
	global_load_dwordx4 v[32:35], v2, s[48:49] offset:3072
	s_and_b32 s56, s38, 7
	s_lshr_b32 s57, s38, 3
	s_sub_i32 s57, s57, 1
	s_lshl_b32 s57, s57, 3
	v_readfirstlane_b32 s100, v162
	s_add_i32 s57, s57, s100
	s_and_b32 s100, s57, 63
	s_lshr_b32 s57, s57, 6
	s_cmp_lt_u32 s100, 32
	s_cbranch_scc0 .Lmy_pfp1_b
	s_and_b32 s101, s56, 1
	s_lshl_b32 s101, s101, 8
	s_lshl_b32 s100, s100, 3
	s_add_i32 s100, s100, s101
	s_mul_i32 s100, s100, 2048
	s_add_u32 s48, s46, 0x7a00000
	s_addc_u32 s49, s47, 0
	s_branch .Lmy_pfp1_j
.Lmy_pfp1_b:
	s_sub_i32 s100, s100, 32
	s_lshr_b32 s101, s56, 1
	s_lshl_b32 s101, s101, 8
	s_lshl_b32 s100, s100, 3
	s_add_i32 s100, s100, s101
	s_mul_i32 s100, s100, 2048
	s_add_u32 s48, s46, 0x3790000
	s_addc_u32 s49, s47, 0
.Lmy_pfp1_j:
	s_add_u32 s48, s48, s100
	s_addc_u32 s49, s49, 0
	s_add_i32 s56, s57, 0
	v_lshrrev_b32_e32 v108, 3, v1
	v_mul_u32_u24_e32 v108, 2048, v108
	v_and_b32_e32 v109, 7, v1
	v_lshl_add_u32 v108, v109, 4, v108
	s_lshl_b32 s34, s5, 12
	s_lshl_b32 s35, s5, 11
	s_lshl_b32 s6, s4, 12
	s_add_u32 s8, s44, s6
	s_addc_u32 s9, s45, 0
	s_lshl_b32 s6, s4, 11
	s_add_u32 s10, s42, s6
	s_addc_u32 s11, s43, 0
	s_mov_b32 s6, s8
	s_mov_b32 s7, s9
	s_mov_b32 s54, s4
	global_load_dwordx4 v[36:39], v2, s[6:7] nt
	global_load_dwordx4 v[40:43], v2, s[6:7] offset:1024 nt
	global_load_dwordx4 v[44:47], v2, s[6:7] offset:2048 nt
	global_load_dwordx4 v[48:51], v2, s[6:7] offset:3072 nt
	s_add_u32 s6, s6, s34
	s_addc_u32 s7, s7, 0
	s_add_i32 s54, s54, s5
	global_load_dwordx4 v[52:55], v2, s[6:7] nt
	global_load_dwordx4 v[56:59], v2, s[6:7] offset:1024 nt
	global_load_dwordx4 v[60:63], v2, s[6:7] offset:2048 nt
	global_load_dwordx4 v[64:67], v2, s[6:7] offset:3072 nt
	s_add_u32 s6, s6, s34
	s_addc_u32 s7, s7, 0
	s_add_i32 s54, s54, s5
	s_waitcnt vmcnt(4)

; DI unsigned cvtpk(float lo, float hi) { f32x2_t v = {lo, hi}; bf16x2_t b = __builtin_convertvector(v, bf16x2_t); return __builtin_bit_cast(unsigned, b); }
; DI void ln_row(float* yrow, bf16_t* xb, const float* g, const float* b, int lane, float* yout = nullptr) {
;     f32x4* xr = (f32x4*)yrow + lane; f32x4* xo = yout ? (f32x4*)yout + lane : xr;
;     f32x4 v[4]; float s = 0.f;
; #pragma unroll
;     for (int j = 0; j < 4; ++j) { v[j] = xr[64 * j]; s += (v[j].x + v[j].y) + (v[j].z + v[j].w); }
;     const float mean = wave_sum(s) * (1.f / DM); float s2 = 0.f;
; #pragma unroll
;     for (int j = 0; j < 4; ++j) { v[j] = v[j] - mean; s2 += (v[j].x * v[j].x + v[j].y * v[j].y) + (v[j].z * v[j].z + v[j].w * v[j].w); }
;     const float rstd = 1.f / sqrtf(wave_sum(s2) * (1.f / DM) + EPS);
;     u32x2* o8 = (u32x2*)xb + lane;
; #pragma unroll
;     for (int j = 0; j < 4; ++j) {
;         const f32x4 gg = ((const f32x4*)g)[lane + 64 * j], bb = ((const f32x4*)b)[lane + 64 * j];
;         const f32x4 o = v[j] * rstd * gg + bb;
;         xo[64 * j] = o;
;         u32x2 w; w.x = cvtpk(o.x, o.y); w.y = cvtpk(o.z, o.w); o8[64 * j] = w;
;     }
.Lmy_lnp1_n0:
	s_add_i32 s100, s56, 0
	s_min_u32 s100, s100, 15
	s_lshl_b32 s100, s100, 7
	s_add_u32 s100, s48, s100
	s_addc_u32 s101, s49, 0
	global_load_dwordx4 v[110:113], v108, s[100:101]
	s_add_i32 s56, s56, 4
	s_waitcnt vmcnt(18)
	v_add_f32_e32 v84, v36, v37
	v_add_f32_e32 v85, v38, v39
	v_add_f32_e32 v86, v40, v41
	v_add_f32_e32 v87, v42, v43
	v_add_f32_e32 v88, v44, v45
	v_add_f32_e32 v89, v46, v47
	v_add_f32_e32 v90, v48, v49
	v_add_f32_e32 v91, v50, v51
	v_add_f32_e32 v84, v84, v85
	v_add_f32_e32 v86, v86, v87
	v_add_f32_e32 v88, v88, v89
	v_add_f32_e32 v90, v90, v91
	v_add_f32_e32 v84, v84, v86
	v_add_f32_e32 v88, v88, v90
	v_add_f32_e32 v84, v84, v88
	s_nop 1
	v_add_f32_dpp v84, v84, v84 quad_perm:[1,0,3,2] row_mask:0xf bank_mask:0xf
	s_nop 1
	v_add_f32_dpp v84, v84, v84 quad_perm:[2,3,0,1] row_mask:0xf bank_mask:0xf
	s_nop 1
	v_add_f32_dpp v84, v84, v84 row_half_mirror row_mask:0xf bank_mask:0xf
	s_nop 1
	v_add_f32_dpp v84, v84, v84 row_mirror row_mask:0xf bank_mask:0xf
	s_nop 1
	v_add_f32_dpp v84, v84, v84 row_bcast:15 row_mask:0xa bank_mask:0xf
	s_nop 1
	v_add_f32_dpp v84, v84, v84 row_bcast:31 row_mask:0xc bank_mask:0xf
	s_nop 1
	v_readlane_b32 s55, v84, 63
	s_nop 1
	v_mov_b32_e32 v85, s55
	v_mul_f32_e32 v85, 0x3a800000, v85
	v_sub_f32_e32 v36, v36, v85
	v_sub_f32_e32 v37, v37, v85
	v_sub_f32_e32 v38, v38, v85
	v_sub_f32_e32 v39, v39, v85
	v_sub_f32_e32 v40, v40, v85
	v_sub_f32_e32 v41, v41, v85
	v_sub_f32_e32 v42, v42, v85
	v_sub_f32_e32 v43, v43, v85
	v_sub_f32_e32 v44, v44, v85
	v_sub_f32_e32 v45, v45, v85
	v_sub_f32_e32 v46, v46, v85
	v_sub_f32_e32 v47, v47, v85
	v_sub_f32_e32 v48, v48, v85
	v_sub_f32_e32 v49, v49, v85
	v_sub_f32_e32 v50, v50, v85
	v_sub_f32_e32 v51, v51, v85
	v_mul_f32_e32 v88, v36, v36
	v_mul_f32_e32 v89, v37, v37
	v_mul_f32_e32 v90, v38, v38
	v_mul_f32_e32 v91, v39, v39
	v_fmac_f32_e32 v88, v40, v40
	v_fmac_f32_e32 v89, v41, v41
	v_fmac_f32_e32 v90, v42, v42
	v_fmac_f32_e32 v91, v43, v43
	v_fmac_f32_e32 v88, v44, v44
	v_fmac_f32_e32 v89, v45, v45
	v_fmac_f32_e32 v90, v46, v46
	v_fmac_f32_e32 v91, v47, v47
	v_fmac_f32_e32 v88, v48, v48
	v_fmac_f32_e32 v89, v49, v49
	v_fmac_f32_e32 v90, v50, v50
	v_fmac_f32_e32 v91, v51, v51
	v_add_f32_e32 v88, v88, v89
	v_add_f32_e32 v90, v90, v91
	v_add_f32_e32 v88, v88, v90
	s_nop 1
	v_add_f32_dpp v88, v88, v88 quad_perm:[1,0,3,2] row_mask:0xf bank_mask:0xf
	s_nop 1
	v_add_f32_dpp v88, v88, v88 quad_perm:[2,3,0,1] row_mask:0xf bank_mask:0xf
	s_nop 1
	v_add_f32_dpp v88, v88, v88 row_half_mirror row_mask:0xf bank_mask:0xf
	s_nop 1
	v_add_f32_dpp v88, v88, v88 row_mirror row_mask:0xf bank_mask:0xf
	s_nop 1
	v_add_f32_dpp v88, v88, v88 row_bcast:15 row_mask:0xa bank_mask:0xf
	s_nop 1
	v_add_f32_dpp v88, v88, v88 row_bcast:31 row_mask:0xc bank_mask:0xf
	s_nop 1
	v_readlane_b32 s55, v88, 63
	s_nop 1
	v_mov_b32_e32 v89, s55
	v_fmamk_f32 v89, v89, 0x3a800000, v214
	v_rsq_f32_e32 v90, v89
	s_nop 0
	v_mul_f32_e32 v91, v89, v90
	v_mul_f32_e32 v91, v91, v90
	v_mul_f32_e32 v91, -0.5, v91
	v_add_f32_e32 v91, 0x3fc00000, v91
	v_mul_f32_e32 v90, v90, v91
	v_pk_mul_f32 v[36:37], v[36:37], v[90:91] op_sel_hi:[1,0]
	v_pk_mul_f32 v[38:39], v[38:39], v[90:91] op_sel_hi:[1,0]
	v_pk_mul_f32 v[40:41], v[40:41], v[90:91] op_sel_hi:[1,0]
	v_pk_mul_f32 v[42:43], v[42:43], v[90:91] op_sel_hi:[1,0]
	v_pk_mul_f32 v[44:45], v[44:45], v[90:91] op_sel_hi:[1,0]
	v_pk_mul_f32 v[46:47], v[46:47], v[90:91] op_sel_hi:[1,0]
	v_pk_mul_f32 v[48:49], v[48:49], v[90:91] op_sel_hi:[1,0]
	v_pk_mul_f32 v[50:51], v[50:51], v[90:91] op_sel_hi:[1,0]
	v_pk_fma_f32 v[36:37], v[36:37], v[4:5], v[20:21]
	v_pk_fma_f32 v[38:39], v[38:39], v[6:7], v[22:23]
	v_pk_fma_f32 v[40:41], v[40:41], v[8:9], v[24:25]
	v_pk_fma_f32 v[42:43], v[42:43], v[10:11], v[26:27]
	v_pk_fma_f32 v[44:45], v[44:45], v[12:13], v[28:29]
	v_pk_fma_f32 v[46:47], v[46:47], v[14:15], v[30:31]
	v_pk_fma_f32 v[48:49], v[48:49], v[16:17], v[32:33]
	v_pk_fma_f32 v[50:51], v[50:51], v[18:19], v[34:35]
	v_cvt_pk_bf16_f32 v100, v36, v37
	v_cvt_pk_bf16_f32 v101, v38, v39
	v_cvt_pk_bf16_f32 v102, v40, v41
	v_cvt_pk_bf16_f32 v103, v42, v43
	v_cvt_pk_bf16_f32 v104, v44, v45
	v_cvt_pk_bf16_f32 v105, v46, v47
	v_cvt_pk_bf16_f32 v106, v48, v49
	v_cvt_pk_bf16_f32 v107, v50, v51
	global_store_dwordx4 v2, v[36:39], s[8:9] nt
	global_store_dwordx4 v2, v[40:43], s[8:9] offset:1024 nt
	global_store_dwordx4 v2, v[44:47], s[8:9] offset:2048 nt
	global_store_dwordx4 v2, v[48:51], s[8:9] offset:3072 nt
	global_store_dwordx2 v3, v[100:101], s[10:11] nt
	global_store_dwordx2 v3, v[102:103], s[10:11] offset:512 nt
	global_store_dwordx2 v3, v[104:105], s[10:11] offset:1024 nt
	global_store_dwordx2 v3, v[106:107], s[10:11] offset:1536 nt
	s_add_u32 s8, s8, s34
	s_addc_u32 s9, s9, 0
	s_add_u32 s10, s10, s35
	s_addc_u32 s11, s11, 0
	s_add_i32 s4, s4, s5
	s_cmp_ge_i32 s4, 0x8000
	s_cbranch_scc1 .Lmy_lnp1_done

; DI unsigned cvtpk(float lo, float hi) { f32x2_t v = {lo, hi}; bf16x2_t b = __builtin_convertvector(v, bf16x2_t); return __builtin_bit_cast(unsigned, b); }
; DI void ln_row(float* yrow, bf16_t* xb, const float* g, const float* b, int lane, float* yout = nullptr) {
;     f32x4* xr = (f32x4*)yrow + lane; f32x4* xo = yout ? (f32x4*)yout + lane : xr;
;     f32x4 v[4]; float s = 0.f;
; #pragma unroll
;     for (int j = 0; j < 4; ++j) { v[j] = xr[64 * j]; s += (v[j].x + v[j].y) + (v[j].z + v[j].w); }
;     const float mean = wave_sum(s) * (1.f / DM); float s2 = 0.f;
; #pragma unroll
;     for (int j = 0; j < 4; ++j) { v[j] = v[j] - mean; s2 += (v[j].x * v[j].x + v[j].y * v[j].y) + (v[j].z * v[j].z + v[j].w * v[j].w); }
;     const float rstd = 1.f / sqrtf(wave_sum(s2) * (1.f / DM) + EPS);
;     u32x2* o8 = (u32x2*)xb + lane;
; #pragma unroll
;     for (int j = 0; j < 4; ++j) {
;         const f32x4 gg = ((const f32x4*)g)[lane + 64 * j], bb = ((const f32x4*)b)[lane + 64 * j];
;         const f32x4 o = v[j] * rstd * gg + bb;
;         xo[64 * j] = o;
;         u32x2 w; w.x = cvtpk(o.x, o.y); w.y = cvtpk(o.z, o.w); o8[64 * j] = w;
;     }
.Lmy_lnp1_n1:
	s_add_i32 s100, s56, 0
	s_min_u32 s100, s100, 15
	s_lshl_b32 s100, s100, 7
	s_add_u32 s100, s48, s100
	s_addc_u32 s101, s49, 0
	global_load_dwordx4 v[110:113], v108, s[100:101]
	s_add_i32 s56, s56, 4
	s_waitcnt vmcnt(18)
	v_add_f32_e32 v84, v52, v53
	v_add_f32_e32 v85, v54, v55
	v_add_f32_e32 v86, v56, v57
	v_add_f32_e32 v87, v58, v59
	v_add_f32_e32 v88, v60, v61
	v_add_f32_e32 v89, v62, v63
	v_add_f32_e32 v90, v64, v65
	v_add_f32_e32 v91, v66, v67
	v_add_f32_e32 v84, v84, v85
	v_add_f32_e32 v86, v86, v87
	v_add_f32_e32 v88, v88, v89
	v_add_f32_e32 v90, v90, v91
	v_add_f32_e32 v84, v84, v86
	v_add_f32_e32 v88, v88, v90
	v_add_f32_e32 v84, v84, v88
	s_nop 1
	v_add_f32_dpp v84, v84, v84 quad_perm:[1,0,3,2] row_mask:0xf bank_mask:0xf
	s_nop 1
	v_add_f32_dpp v84, v84, v84 quad_perm:[2,3,0,1] row_mask:0xf bank_mask:0xf
	s_nop 1
	v_add_f32_dpp v84, v84, v84 row_half_mirror row_mask:0xf bank_mask:0xf
	s_nop 1
	v_add_f32_dpp v84, v84, v84 row_mirror row_mask:0xf bank_mask:0xf
	s_nop 1
	v_add_f32_dpp v84, v84, v84 row_bcast:15 row_mask:0xa bank_mask:0xf
	s_nop 1
	v_add_f32_dpp v84, v84, v84 row_bcast:31 row_mask:0xc bank_mask:0xf
	s_nop 1
	v_readlane_b32 s55, v84, 63
	s_nop 1
	v_mov_b32_e32 v85, s55
	v_mul_f32_e32 v85, 0x3a800000, v85
	v_sub_f32_e32 v52, v52, v85
	v_sub_f32_e32 v53, v53, v85
	v_sub_f32_e32 v54, v54, v85
	v_sub_f32_e32 v55, v55, v85
	v_sub_f32_e32 v56, v56, v85
	v_sub_f32_e32 v57, v57, v85
	v_sub_f32_e32 v58, v58, v85
	v_sub_f32_e32 v59, v59, v85
	v_sub_f32_e32 v60, v60, v85
	v_sub_f32_e32 v61, v61, v85
	v_sub_f32_e32 v62, v62, v85
	v_sub_f32_e32 v63, v63, v85
	v_sub_f32_e32 v64, v64, v85
	v_sub_f32_e32 v65, v65, v85
	v_sub_f32_e32 v66, v66, v85
	v_sub_f32_e32 v67, v67, v85
	v_mul_f32_e32 v88, v52, v52
	v_mul_f32_e32 v89, v53, v53
	v_mul_f32_e32 v90, v54, v54
	v_mul_f32_e32 v91, v55, v55
	v_fmac_f32_e32 v88, v56, v56
	v_fmac_f32_e32 v89, v57, v57
	v_fmac_f32_e32 v90, v58, v58
	v_fmac_f32_e32 v91, v59, v59
	v_fmac_f32_e32 v88, v60, v60
	v_fmac_f32_e32 v89, v61, v61
	v_fmac_f32_e32 v90, v62, v62
	v_fmac_f32_e32 v91, v63, v63
	v_fmac_f32_e32 v88, v64, v64
	v_fmac_f32_e32 v89, v65, v65
	v_fmac_f32_e32 v90, v66, v66
	v_fmac_f32_e32 v91, v67, v67
	v_add_f32_e32 v88, v88, v89
	v_add_f32_e32 v90, v90, v91
	v_add_f32_e32 v88, v88, v90
	s_nop 1
	v_add_f32_dpp v88, v88, v88 quad_perm:[1,0,3,2] row_mask:0xf bank_mask:0xf
	s_nop 1
	v_add_f32_dpp v88, v88, v88 quad_perm:[2,3,0,1] row_mask:0xf bank_mask:0xf
	s_nop 1
	v_add_f32_dpp v88, v88, v88 row_half_mirror row_mask:0xf bank_mask:0xf
	s_nop 1
	v_add_f32_dpp v88, v88, v88 row_mirror row_mask:0xf bank_mask:0xf
	s_nop 1
	v_add_f32_dpp v88, v88, v88 row_bcast:15 row_mask:0xa bank_mask:0xf
	s_nop 1
	v_add_f32_dpp v88, v88, v88 row_bcast:31 row_mask:0xc bank_mask:0xf
	s_nop 1
	v_readlane_b32 s55, v88, 63
	s_nop 1
	v_mov_b32_e32 v89, s55
	v_fmamk_f32 v89, v89, 0x3a800000, v214
	v_rsq_f32_e32 v90, v89
	s_nop 0
	v_mul_f32_e32 v91, v89, v90
	v_mul_f32_e32 v91, v91, v90
	v_mul_f32_e32 v91, -0.5, v91
	v_add_f32_e32 v91, 0x3fc00000, v91
	v_mul_f32_e32 v90, v90, v91
	v_pk_mul_f32 v[52:53], v[52:53], v[90:91] op_sel_hi:[1,0]
	v_pk_mul_f32 v[54:55], v[54:55], v[90:91] op_sel_hi:[1,0]
	v_pk_mul_f32 v[56:57], v[56:57], v[90:91] op_sel_hi:[1,0]
	v_pk_mul_f32 v[58:59], v[58:59], v[90:91] op_sel_hi:[1,0]
	v_pk_mul_f32 v[60:61], v[60:61], v[90:91] op_sel_hi:[1,0]
	v_pk_mul_f32 v[62:63], v[62:63], v[90:91] op_sel_hi:[1,0]
	v_pk_mul_f32 v[64:65], v[64:65], v[90:91] op_sel_hi:[1,0]
	v_pk_mul_f32 v[66:67], v[66:67], v[90:91] op_sel_hi:[1,0]
	v_pk_fma_f32 v[52:53], v[52:53], v[4:5], v[20:21]
	v_pk_fma_f32 v[54:55], v[54:55], v[6:7], v[22:23]
	v_pk_fma_f32 v[56:57], v[56:57], v[8:9], v[24:25]
	v_pk_fma_f32 v[58:59], v[58:59], v[10:11], v[26:27]
	v_pk_fma_f32 v[60:61], v[60:61], v[12:13], v[28:29]
	v_pk_fma_f32 v[62:63], v[62:63], v[14:15], v[30:31]
	v_pk_fma_f32 v[64:65], v[64:65], v[16:17], v[32:33]
	v_pk_fma_f32 v[66:67], v[66:67], v[18:19], v[34:35]
	v_cvt_pk_bf16_f32 v100, v52, v53
	v_cvt_pk_bf16_f32 v101, v54, v55
	v_cvt_pk_bf16_f32 v102, v56, v57
	v_cvt_pk_bf16_f32 v103, v58, v59
	v_cvt_pk_bf16_f32 v104, v60, v61
	v_cvt_pk_bf16_f32 v105, v62, v63
	v_cvt_pk_bf16_f32 v106, v64, v65
	v_cvt_pk_bf16_f32 v107, v66, v67
	global_store_dwordx4 v2, v[52:55], s[8:9] nt
	global_store_dwordx4 v2, v[56:59], s[8:9] offset:1024 nt
	global_store_dwordx4 v2, v[60:63], s[8:9] offset:2048 nt
	global_store_dwordx4 v2, v[64:67], s[8:9] offset:3072 nt
	global_store_dwordx2 v3, v[100:101], s[10:11] nt
	global_store_dwordx2 v3, v[102:103], s[10:11] offset:512 nt
	global_store_dwordx2 v3, v[104:105], s[10:11] offset:1024 nt
	global_store_dwordx2 v3, v[106:107], s[10:11] offset:1536 nt
	s_add_u32 s8, s8, s34
	s_addc_u32 s9, s9, 0
	s_add_u32 s10, s10, s35
	s_addc_u32 s11, s11, 0
	s_add_i32 s4, s4, s5
	s_cmp_ge_i32 s4, 0x8000
	s_cbranch_scc1 .Lmy_lnp1_done

; DI unsigned cvtpk(float lo, float hi) { f32x2_t v = {lo, hi}; bf16x2_t b = __builtin_convertvector(v, bf16x2_t); return __builtin_bit_cast(unsigned, b); }
; DI void ln_row(float* yrow, bf16_t* xb, const float* g, const float* b, int lane, float* yout = nullptr) {
;     f32x4* xr = (f32x4*)yrow + lane; f32x4* xo = yout ? (f32x4*)yout + lane : xr;
;     f32x4 v[4]; float s = 0.f;
; #pragma unroll
;     for (int j = 0; j < 4; ++j) { v[j] = xr[64 * j]; s += (v[j].x + v[j].y) + (v[j].z + v[j].w); }
;     const float mean = wave_sum(s) * (1.f / DM); float s2 = 0.f;
; #pragma unroll
;     for (int j = 0; j < 4; ++j) { v[j] = v[j] - mean; s2 += (v[j].x * v[j].x + v[j].y * v[j].y) + (v[j].z * v[j].z + v[j].w * v[j].w); }
;     const float rstd = 1.f / sqrtf(wave_sum(s2) * (1.f / DM) + EPS);
;     u32x2* o8 = (u32x2*)xb + lane;
; #pragma unroll
;     for (int j = 0; j < 4; ++j) {
;         const f32x4 gg = ((const f32x4*)g)[lane + 64 * j], bb = ((const f32x4*)b)[lane + 64 * j];
;         const f32x4 o = v[j] * rstd * gg + bb;
;         xo[64 * j] = o;
;         u32x2 w; w.x = cvtpk(o.x, o.y); w.y = cvtpk(o.z, o.w); o8[64 * j] = w;
;     }
; DI void ln_phase(unsigned char* lds, int l, int which) {
;     ...
;         int m = gw;
;         for (; m + NGW < MP; m += 2 * NGW) ln_row2(Y + (size_t)m * DM, Y + (size_t)(m + NGW) * DM, XB + (size_t)m * DM, XB + (size_t)(m + NGW) * DM, g, b, lane);
;         if (m < MP) ln_row(Y + (size_t)m * DM, XB + (size_t)m * DM, g, b, lane);
.Lmy_lnp1_n2:
	s_add_i32 s100, s56, 0
	s_min_u32 s100, s100, 15
	s_lshl_b32 s100, s100, 7
	s_add_u32 s100, s48, s100
	s_addc_u32 s101, s49, 0
	global_load_dwordx4 v[110:113], v108, s[100:101]
	s_add_i32 s56, s56, 4
	s_waitcnt vmcnt(18)
	v_add_f32_e32 v84, v68, v69
	v_add_f32_e32 v85, v70, v71
	v_add_f32_e32 v86, v72, v73
	v_add_f32_e32 v87, v74, v75
	v_add_f32_e32 v88, v76, v77
	v_add_f32_e32 v89, v78, v79
	v_add_f32_e32 v90, v80, v81
	v_add_f32_e32 v91, v82, v83
	v_add_f32_e32 v84, v84, v85
	v_add_f32_e32 v86, v86, v87
	v_add_f32_e32 v88, v88, v89
	v_add_f32_e32 v90, v90, v91
	v_add_f32_e32 v84, v84, v86
	v_add_f32_e32 v88, v88, v90
	v_add_f32_e32 v84, v84, v88
	s_nop 1
	v_add_f32_dpp v84, v84, v84 quad_perm:[1,0,3,2] row_mask:0xf bank_mask:0xf
	s_nop 1
	v_add_f32_dpp v84, v84, v84 quad_perm:[2,3,0,1] row_mask:0xf bank_mask:0xf
	s_nop 1
	v_add_f32_dpp v84, v84, v84 row_half_mirror row_mask:0xf bank_mask:0xf
	s_nop 1
	v_add_f32_dpp v84, v84, v84 row_mirror row_mask:0xf bank_mask:0xf
	s_nop 1
	v_add_f32_dpp v84, v84, v84 row_bcast:15 row_mask:0xa bank_mask:0xf
	s_nop 1
	v_add_f32_dpp v84, v84, v84 row_bcast:31 row_mask:0xc bank_mask:0xf
	s_nop 1
	v_readlane_b32 s55, v84, 63
	s_nop 1
	v_mov_b32_e32 v85, s55
	v_mul_f32_e32 v85, 0x3a800000, v85
	v_sub_f32_e32 v68, v68, v85
	v_sub_f32_e32 v69, v69, v85
	v_sub_f32_e32 v70, v70, v85
	v_sub_f32_e32 v71, v71, v85
	v_sub_f32_e32 v72, v72, v85
	v_sub_f32_e32 v73, v73, v85
	v_sub_f32_e32 v74, v74, v85
	v_sub_f32_e32 v75, v75, v85
	v_sub_f32_e32 v76, v76, v85
	v_sub_f32_e32 v77, v77, v85
	v_sub_f32_e32 v78, v78, v85
	v_sub_f32_e32 v79, v79, v85
	v_sub_f32_e32 v80, v80, v85
	v_sub_f32_e32 v81, v81, v85
	v_sub_f32_e32 v82, v82, v85
	v_sub_f32_e32 v83, v83, v85
	v_mul_f32_e32 v88, v68, v68
	v_mul_f32_e32 v89, v69, v69
	v_mul_f32_e32 v90, v70, v70
	v_mul_f32_e32 v91, v71, v71
	v_fmac_f32_e32 v88, v72, v72
	v_fmac_f32_e32 v89, v73, v73
	v_fmac_f32_e32 v90, v74, v74
	v_fmac_f32_e32 v91, v75, v75
	v_fmac_f32_e32 v88, v76, v76
	v_fmac_f32_e32 v89, v77, v77
	v_fmac_f32_e32 v90, v78, v78
	v_fmac_f32_e32 v91, v79, v79
	v_fmac_f32_e32 v88, v80, v80
	v_fmac_f32_e32 v89, v81, v81
	v_fmac_f32_e32 v90, v82, v82
	v_fmac_f32_e32 v91, v83, v83
	v_add_f32_e32 v88, v88, v89
	v_add_f32_e32 v90, v90, v91
	v_add_f32_e32 v88, v88, v90
	s_nop 1
	v_add_f32_dpp v88, v88, v88 quad_perm:[1,0,3,2] row_mask:0xf bank_mask:0xf
	s_nop 1
	v_add_f32_dpp v88, v88, v88 quad_perm:[2,3,0,1] row_mask:0xf bank_mask:0xf
	s_nop 1
	v_add_f32_dpp v88, v88, v88 row_half_mirror row_mask:0xf bank_mask:0xf
	s_nop 1
	v_add_f32_dpp v88, v88, v88 row_mirror row_mask:0xf bank_mask:0xf
	s_nop 1
	v_add_f32_dpp v88, v88, v88 row_bcast:15 row_mask:0xa bank_mask:0xf
	s_nop 1
	v_add_f32_dpp v88, v88, v88 row_bcast:31 row_mask:0xc bank_mask:0xf
	s_nop 1
	v_readlane_b32 s55, v88, 63
	s_nop 1
	v_mov_b32_e32 v89, s55
	v_fmamk_f32 v89, v89, 0x3a800000, v214
	v_rsq_f32_e32 v90, v89
	s_nop 0
	v_mul_f32_e32 v91, v89, v90
	v_mul_f32_e32 v91, v91, v90
	v_mul_f32_e32 v91, -0.5, v91
	v_add_f32_e32 v91, 0x3fc00000, v91
	v_mul_f32_e32 v90, v90, v91
	v_pk_mul_f32 v[68:69], v[68:69], v[90:91] op_sel_hi:[1,0]
	v_pk_mul_f32 v[70:71], v[70:71], v[90:91] op_sel_hi:[1,0]
	v_pk_mul_f32 v[72:73], v[72:73], v[90:91] op_sel_hi:[1,0]
	v_pk_mul_f32 v[74:75], v[74:75], v[90:91] op_sel_hi:[1,0]
	v_pk_mul_f32 v[76:77], v[76:77], v[90:91] op_sel_hi:[1,0]
	v_pk_mul_f32 v[78:79], v[78:79], v[90:91] op_sel_hi:[1,0]
	v_pk_mul_f32 v[80:81], v[80:81], v[90:91] op_sel_hi:[1,0]
	v_pk_mul_f32 v[82:83], v[82:83], v[90:91] op_sel_hi:[1,0]
	v_pk_fma_f32 v[68:69], v[68:69], v[4:5], v[20:21]
	v_pk_fma_f32 v[70:71], v[70:71], v[6:7], v[22:23]
	v_pk_fma_f32 v[72:73], v[72:73], v[8:9], v[24:25]
	v_pk_fma_f32 v[74:75], v[74:75], v[10:11], v[26:27]
	v_pk_fma_f32 v[76:77], v[76:77], v[12:13], v[28:29]
	v_pk_fma_f32 v[78:79], v[78:79], v[14:15], v[30:31]
	v_pk_fma_f32 v[80:81], v[80:81], v[16:17], v[32:33]
	v_pk_fma_f32 v[82:83], v[82:83], v[18:19], v[34:35]
	v_cvt_pk_bf16_f32 v100, v68, v69
	v_cvt_pk_bf16_f32 v101, v70, v71
	v_cvt_pk_bf16_f32 v102, v72, v73
	v_cvt_pk_bf16_f32 v103, v74, v75
	v_cvt_pk_bf16_f32 v104, v76, v77
	v_cvt_pk_bf16_f32 v105, v78, v79
	v_cvt_pk_bf16_f32 v106, v80, v81
	v_cvt_pk_bf16_f32 v107, v82, v83
	global_store_dwordx4 v2, v[68:71], s[8:9] nt
	global_store_dwordx4 v2, v[72:75], s[8:9] offset:1024 nt
	global_store_dwordx4 v2, v[76:79], s[8:9] offset:2048 nt
	global_store_dwordx4 v2, v[80:83], s[8:9] offset:3072 nt
	global_store_dwordx2 v3, v[100:101], s[10:11] nt
	global_store_dwordx2 v3, v[102:103], s[10:11] offset:512 nt
	global_store_dwordx2 v3, v[104:105], s[10:11] offset:1024 nt
	global_store_dwordx2 v3, v[106:107], s[10:11] offset:1536 nt
	s_add_u32 s8, s8, s34
	s_addc_u32 s9, s9, 0
	s_add_u32 s10, s10, s35
	s_addc_u32 s11, s11, 0
	s_add_i32 s4, s4, s5
	s_cmp_ge_i32 s4, 0x8000
	s_cbranch_scc1 .Lmy_lnp1_done
	s_branch .Lmy_lnp1_b0
.Lmy_lnp1_done:
.LBB0_2135:
	s_or_b64 exec, exec, s[50:51]
	s_mov_b64 s[40:41], 0

; #define PHASE_BEGIN KArg pp = kargs(); unsigned char* ws = pp->ws; int ll = l; asm volatile("" : "+s"(ll)); (void)ws; (void)ll;
; DI void ln_phase(unsigned char* lds, int l, int which) {
;     PHASE_BEGIN
;     int tid_l = threadIdx.x; asm volatile("" : "+v"(tid_l));
;     int bid_l = blockIdx.x; asm volatile("" : "+s"(bid_l));
;     const int lane = tid_l & 63, wid = tid_l >> 6, bid = bid_l;
;     const float* g = pp->in[23] + ((size_t)ll * 3 + which) * DM; const float* b = pp->in[24] + ((size_t)ll * 3 + which) * DM;
;     float* Y = B_Y; bf16_t* XB = B_XB;
;     ...
;     } else {
;         const int gw = (bid - 8) * 8 + wid, NGW = ((int)gridDim.x - 8) * 8;
;         if (REPS(3) > 1) for (int m = gw; m < MP; m += NGW) ln_row(Y + (size_t)m * DM, (bf16_t*)(ws + WS_OG) + (size_t)m * DM, g, b, lane, (float*)(ws + WS_BIG) + (size_t)m * DM);
;         int m = gw;
.LBB0_2398:
	s_or_b64 exec, exec, s[34:35]
	s_mov_b64 s[4:5], s[90:91]
	s_waitcnt lgkmcnt(0)
	s_barrier
	s_load_dwordx8 s[40:47], s[4:5], 0xb8
	v_readlane_b32 s5, v247, 50
	s_mul_hi_i32 s4, s5, 0x3000
	v_mov_b32_e32 v163, v212
	v_writelane_b32 v247, s5, 50
	s_mulk_i32 s5, 0x3000
	s_add_u32 s5, s5, 0x2000
	s_addc_u32 s4, s4, 0
	s_waitcnt lgkmcnt(0)
	s_add_u32 s56, s40, s5
	s_addc_u32 s57, s41, s4
	s_add_u32 s48, s42, s5
	s_mov_b32 s70, s2
	s_addc_u32 s49, s43, s4
	s_cmp_gt_i32 s70, 7
	v_and_b32_e32 v1, 63, v163
	v_ashrrev_i32_e32 v162, 6, v163
	s_mov_b64 s[40:41], -1
	s_cbranch_scc0 .LBB0_2406
	s_mov_b64 s[50:51], exec
	s_add_u32 s42, s46, 0x3a00000
	s_addc_u32 s43, s47, 0
	v_readfirstlane_b32 s4, v162
	s_lshl_b32 s6, s70, 3
	s_add_i32 s4, s4, s6
	s_sub_i32 s4, s4, 64
	v_readlane_b32 s5, v247, 49
	v_lshlrev_b32_e32 v2, 4, v1
	v_lshlrev_b32_e32 v3, 3, v1
	global_load_dwordx4 v[4:7], v2, s[56:57]
	global_load_dwordx4 v[8:11], v2, s[56:57] offset:1024
	global_load_dwordx4 v[12:15], v2, s[56:57] offset:2048
	global_load_dwordx4 v[16:19], v2, s[56:57] offset:3072
	global_load_dwordx4 v[20:23], v2, s[48:49]
	global_load_dwordx4 v[24:27], v2, s[48:49] offset:1024
	global_load_dwordx4 v[28:31], v2, s[48:49] offset:2048
	global_load_dwordx4 v[32:35], v2, s[48:49] offset:3072
	s_and_b32 s56, s70, 7
	s_lshr_b32 s57, s70, 3
	s_sub_i32 s57, s57, 1
	s_lshl_b32 s57, s57, 3
	v_readfirstlane_b32 s100, v162
	s_add_i32 s57, s57, s100
	s_and_b32 s100, s57, 63
	s_lshr_b32 s57, s57, 6
	s_cmp_lt_u32 s100, 32
	s_cbranch_scc0 .Lmy_pfp2_b
	s_and_b32 s101, s56, 1
	s_lshl_b32 s101, s101, 8
	s_lshl_b32 s100, s100, 3
	s_add_i32 s100, s100, s101
	s_mul_i32 s100, s100, 5632
	s_add_u32 s48, s46, 0x1b400000
	s_addc_u32 s49, s47, 0
	s_branch .Lmy_pfp2_j
.Lmy_pfp2_b:
	s_sub_i32 s100, s100, 32
	s_lshr_b32 s101, s56, 1
	s_lshl_b32 s101, s101, 8
	s_lshl_b32 s100, s100, 3
	s_add_i32 s100, s100, s101
	s_mul_i32 s100, s100, 5632
	s_add_u32 s48, s46, 0x1c80000
	s_addc_u32 s49, s47, 0
